# ffn_act load balance: the partial third round (98304 thread-items) spread over threads 0-383 of all 256 workgroups instead of workgroups 0-191 only
# baseline (speedup 1.0000x reference)
.LBB0_294:
	s_andn2_b64 vcc, exec, s[0:1]
	s_cbranch_vccnz .LBB0_358
	v_mov_b32_e32 v0, v192
	s_mov_b64 s[0:1], 0x58000
	v_ashrrev_i32_e32 v1, 31, v0
	v_lshl_add_u64 v[118:119], s[82:83], 0, v[0:1]
	v_cmp_gt_u64_e32 vcc, s[0:1], v[118:119]
	s_and_saveexec_b64 s[8:9], vcc
	s_mov_b32 s18, 0xb000
	s_cbranch_execz .LBB0_306
	s_mov_b64 s[4:5], s[38:39]
	v_readlane_b32 s36, v254, 10
	s_mul_i32 s1, s61, 0x10800
	v_readlane_b32 s48, v254, 22
	s_mul_hi_i32 s0, s61, 0x10800
	v_readlane_b32 s49, v254, 23
	s_add_u32 s10, s48, s1
	v_readlane_b32 s50, v254, 24
	s_addc_u32 s11, s49, s0
	s_mul_i32 s1, s61, 0x5800
	v_readlane_b32 s40, v254, 14
	v_readlane_b32 s41, v254, 15
	v_readlane_b32 s42, v254, 16
	v_readlane_b32 s43, v254, 17
	v_readlane_b32 s44, v254, 18
	v_readlane_b32 s45, v254, 19
	v_readlane_b32 s46, v254, 20
	v_readlane_b32 s47, v254, 21
	v_readlane_b32 s51, v254, 25
	s_mul_hi_i32 s0, s61, 0x5800
	s_add_u32 s14, s50, s1
	v_readlane_b32 s38, v254, 12
	v_readlane_b32 s39, v254, 13
	s_addc_u32 s15, s51, s0
	v_readlane_b32 s40, v254, 43
	s_mov_b64 s[38:39], s[4:5]
	v_readlane_b32 s41, v254, 44
	v_readlane_b32 s42, v254, 45
	v_readlane_b32 s43, v254, 46
	v_readlane_b32 s44, v254, 47
	v_readlane_b32 s45, v254, 48
	v_readlane_b32 s50, v254, 53
	v_readlane_b32 s51, v254, 54
	v_readlane_b32 s52, v254, 55
	v_readlane_b32 s53, v254, 56
	s_mov_b64 s[16:17], 0
	v_readlane_b32 s37, v254, 11
	v_readlane_b32 s46, v254, 49
	v_readlane_b32 s47, v254, 50
	v_readlane_b32 s48, v254, 51
	v_readlane_b32 s49, v254, 52
	v_readlane_b32 s54, v254, 57
	v_readlane_b32 s55, v254, 58
	v_mov_b32_e32 v214, 0x7fffffff
	v_mov_b32_e32 v215, -1
	s_cmp_eq_u32 s38, 0x20000
	s_cbranch_scc0 .Lff_nobal
	v_mov_b32_e32 v215, 0x40000
	s_lshr_b32 s0, s82, 9
	s_mul_i32 s0, s0, 0x180
	s_add_i32 s0, s0, 0x40000
	v_add_u32_e32 v216, s0, v192
	v_cmp_gt_u32_e32 vcc, 0x180, v192
	s_nop 1
	v_cndmask_b32_e32 v214, v214, v216, vcc

.LBB0_297:
	s_or_b64 exec, exec, s[0:1]
	v_pk_mul_f32 v[120:121], v[36:37], v[114:115]
	s_waitcnt vmcnt(0)
	v_lshlrev_b32_e32 v138, 16, v88
	v_and_b32_e32 v139, 0xffff0000, v88
	v_pk_fma_f32 v[120:121], v[32:33], v[130:131], v[120:121]
	v_pk_mul_f32 v[140:141], v[56:57], v[110:111]
	v_pk_fma_f32 v[120:121], v[44:45], v[138:139], v[120:121]
	v_lshlrev_b32_e32 v136, 16, v92
	v_pk_add_f32 v[120:121], v[52:53], v[120:121]
	v_and_b32_e32 v137, 0xffff0000, v92
	v_mul_f32_e32 v88, 0xbfb8aa3b, v120
	v_exp_f32_e32 v88, v88
	v_pk_fma_f32 v[126:127], v[40:41], v[126:127], v[140:141]
	s_mov_b32 s0, 0x10000
	v_pk_fma_f32 v[126:127], v[60:61], v[136:137], v[126:127]
	v_add_f32_e32 v88, 1.0, v88
	v_rcp_f32_e32 v130, v88
	v_mul_f32_e32 v88, 0xbfb8aa3b, v121
	v_exp_f32_e32 v88, v88
	v_pk_add_f32 v[126:127], v[64:65], v[126:127]
	v_lshl_add_u64 v[118:119], v[118:119], 0, s[38:39]
	v_add_f32_e32 v88, 1.0, v88
	v_rcp_f32_e32 v131, v88
	s_nop 0
	v_pk_mul_f32 v[120:121], v[120:121], v[130:131]
	s_nop 0
	v_pk_mul_f32 v[140:141], v[126:127], v[120:121]
	v_pk_mul_f32 v[120:121], v[38:39], v[108:109]
	v_lshlrev_b32_e32 v130, 16, v89
	v_and_b32_e32 v131, 0xffff0000, v89
	v_pk_fma_f32 v[88:89], v[34:35], v[134:135], v[120:121]
	v_lshlrev_b32_e32 v134, 16, v93
	v_pk_fma_f32 v[88:89], v[46:47], v[130:131], v[88:89]
	v_and_b32_e32 v135, 0xffff0000, v93
	v_pk_add_f32 v[88:89], v[54:55], v[88:89]
	v_pk_mul_f32 v[126:127], v[58:59], v[106:107]
	v_mul_f32_e32 v92, 0xbfb8aa3b, v88
	v_mul_f32_e32 v93, 0xbfb8aa3b, v89
	v_exp_f32_e32 v92, v92
	v_exp_f32_e32 v93, v93
	v_pk_fma_f32 v[120:121], v[42:43], v[132:133], v[126:127]
	v_lshlrev_b32_e32 v126, 16, v90
	v_add_f32_e32 v92, 1.0, v92
	v_add_f32_e32 v93, 1.0, v93
	v_rcp_f32_e32 v92, v92
	v_rcp_f32_e32 v93, v93
	v_pk_fma_f32 v[120:121], v[62:63], v[134:135], v[120:121]
	v_and_b32_e32 v127, 0xffff0000, v90
	v_pk_add_f32 v[120:121], v[66:67], v[120:121]
	v_pk_mul_f32 v[88:89], v[88:89], v[92:93]
	s_nop 0
	v_pk_mul_f32 v[92:93], v[120:121], v[88:89]
	v_pk_mul_f32 v[88:89], v[4:5], v[104:105]
	v_pk_mul_f32 v[120:121], v[20:21], v[102:103]
	v_pk_fma_f32 v[88:89], v[0:1], v[128:129], v[88:89]
	v_lshlrev_b32_e32 v128, 16, v94
	v_pk_fma_f32 v[88:89], v[12:13], v[126:127], v[88:89]
	v_and_b32_e32 v129, 0xffff0000, v94
	v_pk_add_f32 v[88:89], v[16:17], v[88:89]
	v_pk_fma_f32 v[120:121], v[8:9], v[124:125], v[120:121]
	v_mul_f32_e32 v90, 0xbfb8aa3b, v88
	v_exp_f32_e32 v90, v90
	v_pk_fma_f32 v[120:121], v[24:25], v[128:129], v[120:121]
	v_add_f32_e32 v90, 1.0, v90
	v_rcp_f32_e32 v132, v90
	v_mul_f32_e32 v90, 0xbfb8aa3b, v89
	v_exp_f32_e32 v90, v90
	v_pk_add_f32 v[120:121], v[28:29], v[120:121]
	v_add_f32_e32 v90, 1.0, v90
	v_rcp_f32_e32 v133, v90
	s_nop 0
	v_pk_mul_f32 v[88:89], v[88:89], v[132:133]
	s_nop 0
	v_pk_mul_f32 v[124:125], v[120:121], v[88:89]
	v_pk_mul_f32 v[88:89], v[6:7], v[98:99]
	v_lshlrev_b32_e32 v120, 16, v91
	v_and_b32_e32 v121, 0xffff0000, v91
	v_pk_fma_f32 v[88:89], v[2:3], v[122:123], v[88:89]
	v_pk_mul_f32 v[132:133], v[22:23], v[96:97]
	v_pk_fma_f32 v[88:89], v[14:15], v[120:121], v[88:89]
	v_lshlrev_b32_e32 v122, 16, v95
	v_pk_add_f32 v[88:89], v[18:19], v[88:89]
	v_and_b32_e32 v123, 0xffff0000, v95
	v_mul_f32_e32 v90, 0xbfb8aa3b, v88
	v_mul_f32_e32 v91, 0xbfb8aa3b, v89
	v_exp_f32_e32 v90, v90
	v_exp_f32_e32 v91, v91
	v_pk_fma_f32 v[94:95], v[10:11], v[116:117], v[132:133]
	v_add_f32_e32 v90, 1.0, v90
	v_add_f32_e32 v91, 1.0, v91
	v_rcp_f32_e32 v90, v90
	v_rcp_f32_e32 v91, v91
	v_pk_fma_f32 v[94:95], v[26:27], v[122:123], v[94:95]
	v_pk_mul_f32 v[88:89], v[88:89], v[90:91]
	v_pk_add_f32 v[94:95], v[30:31], v[94:95]
	v_cvt_pk_bf16_f32 v90, v124, v125
	v_pk_mul_f32 v[94:95], v[94:95], v[88:89]
	v_cvt_pk_bf16_f32 v89, v92, v93
	v_add_co_u32_e32 v92, vcc, s0, v100
	v_cvt_pk_bf16_f32 v88, v140, v141
	v_cvt_pk_bf16_f32 v91, v94, v95
	v_addc_co_u32_e32 v93, vcc, 0, v101, vcc
	global_store_dwordx4 v[92:93], v[88:91], off offset:2048
	v_pk_mul_f32 v[94:95], v[56:57], v[136:137]
	s_mov_b32 s0, 0x11000
	v_pk_mul_f32 v[88:89], v[36:37], v[138:139]
	v_lshlrev_b32_e32 v90, 16, v84
	v_and_b32_e32 v91, 0xffff0000, v84
	v_pk_fma_f32 v[88:89], v[32:33], v[114:115], v[88:89]
	v_lshlrev_b32_e32 v114, 16, v80
	v_pk_fma_f32 v[88:89], v[44:45], v[90:91], v[88:89]
	v_and_b32_e32 v115, 0xffff0000, v80
	v_pk_add_f32 v[88:89], v[52:53], v[88:89]
	v_pk_fma_f32 v[94:95], v[40:41], v[110:111], v[94:95]
	v_mul_f32_e32 v84, 0xbfb8aa3b, v88
	v_mul_f32_e32 v80, 0xbfb8aa3b, v89
	v_exp_f32_e32 v84, v84
	v_exp_f32_e32 v80, v80
	v_pk_fma_f32 v[94:95], v[60:61], v[114:115], v[94:95]
	v_add_f32_e32 v84, 1.0, v84
	v_add_f32_e32 v80, 1.0, v80
	v_rcp_f32_e32 v92, v84
	v_rcp_f32_e32 v93, v80
	v_pk_add_f32 v[94:95], v[64:65], v[94:95]
	v_pk_mul_f32 v[88:89], v[88:89], v[92:93]
	s_nop 0
	v_pk_mul_f32 v[110:111], v[94:95], v[88:89]
	v_lshlrev_b32_e32 v88, 16, v85
	v_and_b32_e32 v89, 0xffff0000, v85
	v_pk_mul_f32 v[84:85], v[38:39], v[130:131]
	v_lshlrev_b32_e32 v94, 16, v81
	v_pk_fma_f32 v[84:85], v[34:35], v[108:109], v[84:85]
	v_and_b32_e32 v95, 0xffff0000, v81
	v_pk_fma_f32 v[84:85], v[46:47], v[88:89], v[84:85]
	v_pk_mul_f32 v[92:93], v[58:59], v[134:135]
	v_pk_add_f32 v[84:85], v[54:55], v[84:85]
	v_pk_fma_f32 v[92:93], v[42:43], v[106:107], v[92:93]
	v_mul_f32_e32 v80, 0xbfb8aa3b, v84
	v_mul_f32_e32 v81, 0xbfb8aa3b, v85
	v_exp_f32_e32 v80, v80
	v_exp_f32_e32 v81, v81
	v_pk_fma_f32 v[92:93], v[62:63], v[94:95], v[92:93]
	v_pk_mul_f32 v[108:109], v[20:21], v[128:129]
	v_add_f32_e32 v80, 1.0, v80
	v_add_f32_e32 v81, 1.0, v81
	v_rcp_f32_e32 v80, v80
	v_rcp_f32_e32 v81, v81
	v_pk_add_f32 v[92:93], v[66:67], v[92:93]
	v_pk_fma_f32 v[102:103], v[8:9], v[102:103], v[108:109]
	v_pk_mul_f32 v[80:81], v[84:85], v[80:81]
	s_nop 0
	v_pk_mul_f32 v[106:107], v[92:93], v[80:81]
	v_pk_mul_f32 v[80:81], v[4:5], v[126:127]
	v_lshlrev_b32_e32 v84, 16, v86
	v_and_b32_e32 v85, 0xffff0000, v86
	v_pk_fma_f32 v[80:81], v[0:1], v[104:105], v[80:81]
	v_lshlrev_b32_e32 v92, 16, v82
	v_pk_fma_f32 v[80:81], v[12:13], v[84:85], v[80:81]
	v_and_b32_e32 v93, 0xffff0000, v82
	v_pk_add_f32 v[80:81], v[16:17], v[80:81]
	v_pk_fma_f32 v[102:103], v[24:25], v[92:93], v[102:103]
	v_mul_f32_e32 v86, 0xbfb8aa3b, v80
	v_mul_f32_e32 v82, 0xbfb8aa3b, v81
	v_exp_f32_e32 v86, v86
	v_exp_f32_e32 v82, v82
	v_pk_add_f32 v[102:103], v[28:29], v[102:103]
	v_pk_mul_f32 v[116:117], v[20:21], v[92:93]
	v_add_f32_e32 v86, 1.0, v86
	v_add_f32_e32 v82, 1.0, v82
	v_rcp_f32_e32 v104, v86
	v_rcp_f32_e32 v105, v82
	v_pk_fma_f32 v[116:117], v[8:9], v[128:129], v[116:117]
	v_pk_mul_f32 v[80:81], v[80:81], v[104:105]
	s_nop 0
	v_pk_mul_f32 v[102:103], v[102:103], v[80:81]
	v_lshlrev_b32_e32 v80, 16, v87
	v_and_b32_e32 v81, 0xffff0000, v87
	v_pk_mul_f32 v[86:87], v[6:7], v[120:121]
	v_pk_mul_f32 v[104:105], v[22:23], v[122:123]
	v_pk_fma_f32 v[86:87], v[2:3], v[98:99], v[86:87]
	v_pk_fma_f32 v[96:97], v[10:11], v[96:97], v[104:105]
	v_pk_fma_f32 v[86:87], v[14:15], v[80:81], v[86:87]
	v_lshlrev_b32_e32 v104, 16, v72
	v_pk_add_f32 v[86:87], v[18:19], v[86:87]
	v_and_b32_e32 v105, 0xffff0000, v72
	v_mul_f32_e32 v82, 0xbfb8aa3b, v86
	v_mul_f32_e32 v99, 0xbfb8aa3b, v87
	v_exp_f32_e32 v82, v82
	v_exp_f32_e32 v99, v99
	v_add_f32_e32 v82, 1.0, v82
	v_add_f32_e32 v99, 1.0, v99
	v_rcp_f32_e32 v98, v82
	v_rcp_f32_e32 v99, v99
	v_lshlrev_b32_e32 v82, 16, v83
	v_and_b32_e32 v83, 0xffff0000, v83
	v_pk_fma_f32 v[96:97], v[26:27], v[82:83], v[96:97]
	v_pk_mul_f32 v[86:87], v[86:87], v[98:99]
	v_pk_add_f32 v[96:97], v[30:31], v[96:97]
	v_cvt_pk_bf16_f32 v98, v102, v103
	v_pk_mul_f32 v[86:87], v[96:97], v[86:87]
	v_cvt_pk_bf16_f32 v96, v110, v111
	v_cvt_pk_bf16_f32 v99, v86, v87
	v_add_co_u32_e32 v86, vcc, s0, v100
	v_cvt_pk_bf16_f32 v97, v106, v107
	s_nop 0
	v_addc_co_u32_e32 v87, vcc, 0, v101, vcc
	global_store_dwordx4 v[86:87], v[96:99], off offset:3584
	v_pk_mul_f32 v[86:87], v[36:37], v[90:91]
	v_pk_mul_f32 v[102:103], v[56:57], v[114:115]
	v_lshlrev_b32_e32 v96, 16, v76
	v_and_b32_e32 v97, 0xffff0000, v76
	v_pk_fma_f32 v[86:87], v[32:33], v[138:139], v[86:87]
	v_pk_fma_f32 v[102:103], v[40:41], v[136:137], v[102:103]
	v_pk_fma_f32 v[86:87], v[44:45], v[96:97], v[86:87]
	v_pk_fma_f32 v[102:103], v[60:61], v[104:105], v[102:103]
	v_pk_add_f32 v[86:87], v[52:53], v[86:87]
	v_pk_add_f32 v[102:103], v[64:65], v[102:103]
	v_mul_f32_e32 v76, 0xbfb8aa3b, v86
	v_mul_f32_e32 v72, 0xbfb8aa3b, v87
	v_exp_f32_e32 v76, v76
	v_exp_f32_e32 v72, v72
	s_mov_b32 s0, 0x13000
	v_pk_mul_f32 v[36:37], v[36:37], v[96:97]
	v_add_f32_e32 v76, 1.0, v76
	v_add_f32_e32 v72, 1.0, v72
	v_rcp_f32_e32 v98, v76
	v_rcp_f32_e32 v99, v72
	v_pk_fma_f32 v[32:33], v[32:33], v[90:91], v[36:37]
	v_pk_mul_f32 v[86:87], v[86:87], v[98:99]
	s_nop 0
	v_pk_mul_f32 v[106:107], v[102:103], v[86:87]
	v_lshlrev_b32_e32 v86, 16, v77
	v_and_b32_e32 v87, 0xffff0000, v77
	v_pk_mul_f32 v[76:77], v[38:39], v[88:89]
	v_lshlrev_b32_e32 v102, 16, v73
	v_pk_fma_f32 v[76:77], v[34:35], v[130:131], v[76:77]
	v_and_b32_e32 v103, 0xffff0000, v73
	v_pk_fma_f32 v[76:77], v[46:47], v[86:87], v[76:77]
	v_pk_mul_f32 v[98:99], v[58:59], v[94:95]
	v_pk_add_f32 v[76:77], v[54:55], v[76:77]
	v_pk_fma_f32 v[98:99], v[42:43], v[134:135], v[98:99]
	v_mul_f32_e32 v72, 0xbfb8aa3b, v76
	v_mul_f32_e32 v73, 0xbfb8aa3b, v77
	v_exp_f32_e32 v72, v72
	v_exp_f32_e32 v73, v73
	v_pk_fma_f32 v[98:99], v[62:63], v[102:103], v[98:99]
	v_cvt_pk_bf16_f32 v106, v106, v107
	v_add_f32_e32 v72, 1.0, v72
	v_add_f32_e32 v73, 1.0, v73
	v_rcp_f32_e32 v72, v72
	v_rcp_f32_e32 v73, v73
	v_pk_add_f32 v[98:99], v[66:67], v[98:99]
	v_pk_mul_f32 v[38:39], v[38:39], v[86:87]
	v_pk_mul_f32 v[72:73], v[76:77], v[72:73]
	s_nop 0
	v_pk_mul_f32 v[108:109], v[98:99], v[72:73]
	v_pk_mul_f32 v[72:73], v[4:5], v[84:85]
	v_lshlrev_b32_e32 v76, 16, v78
	v_and_b32_e32 v77, 0xffff0000, v78
	v_pk_fma_f32 v[72:73], v[0:1], v[126:127], v[72:73]
	v_lshlrev_b32_e32 v98, 16, v74
	v_pk_fma_f32 v[72:73], v[12:13], v[76:77], v[72:73]
	v_and_b32_e32 v99, 0xffff0000, v74
	v_pk_add_f32 v[72:73], v[16:17], v[72:73]
	v_pk_fma_f32 v[116:117], v[24:25], v[98:99], v[116:117]
	v_mul_f32_e32 v78, 0xbfb8aa3b, v72
	v_mul_f32_e32 v74, 0xbfb8aa3b, v73
	v_exp_f32_e32 v78, v78
	v_exp_f32_e32 v74, v74
	v_pk_add_f32 v[116:117], v[28:29], v[116:117]
	v_cvt_pk_bf16_f32 v107, v108, v109
	v_add_f32_e32 v78, 1.0, v78
	v_add_f32_e32 v74, 1.0, v74
	v_rcp_f32_e32 v110, v78
	v_rcp_f32_e32 v111, v74
	v_pk_fma_f32 v[34:35], v[34:35], v[88:89], v[38:39]
	v_pk_mul_f32 v[4:5], v[4:5], v[76:77]
	v_lshlrev_b32_e32 v38, 16, v49
	v_pk_mul_f32 v[72:73], v[72:73], v[110:111]
	v_pk_fma_f32 v[0:1], v[0:1], v[84:85], v[4:5]
	v_pk_mul_f32 v[110:111], v[116:117], v[72:73]
	v_lshlrev_b32_e32 v72, 16, v79
	v_and_b32_e32 v73, 0xffff0000, v79
	v_pk_mul_f32 v[78:79], v[6:7], v[80:81]
	v_cvt_pk_bf16_f32 v108, v110, v111
	v_pk_fma_f32 v[78:79], v[2:3], v[120:121], v[78:79]
	v_pk_mul_f32 v[120:121], v[22:23], v[82:83]
	v_pk_fma_f32 v[78:79], v[14:15], v[72:73], v[78:79]
	v_pk_fma_f32 v[120:121], v[10:11], v[122:123], v[120:121]
	v_pk_add_f32 v[78:79], v[18:19], v[78:79]
	v_pk_mul_f32 v[6:7], v[6:7], v[72:73]
	v_mul_f32_e32 v74, 0xbfb8aa3b, v78
	v_mul_f32_e32 v113, 0xbfb8aa3b, v79
	v_exp_f32_e32 v74, v74
	v_exp_f32_e32 v113, v113
	v_pk_fma_f32 v[2:3], v[2:3], v[80:81], v[6:7]
	v_and_b32_e32 v39, 0xffff0000, v49
	v_add_f32_e32 v74, 1.0, v74
	v_add_f32_e32 v113, 1.0, v113
	v_rcp_f32_e32 v116, v74
	v_rcp_f32_e32 v117, v113
	v_lshlrev_b32_e32 v74, 16, v75
	v_and_b32_e32 v75, 0xffff0000, v75
	v_pk_fma_f32 v[120:121], v[26:27], v[74:75], v[120:121]
	v_pk_mul_f32 v[78:79], v[78:79], v[116:117]
	v_pk_add_f32 v[120:121], v[30:31], v[120:121]
	v_lshlrev_b32_e32 v6, 16, v51
	v_pk_mul_f32 v[78:79], v[120:121], v[78:79]
	v_and_b32_e32 v7, 0xffff0000, v51
	v_cvt_pk_bf16_f32 v109, v78, v79
	v_add_co_u32_e32 v78, vcc, s0, v100
	s_mov_b64 s[0:1], 0x57fff
	s_nop 0
	v_addc_co_u32_e32 v79, vcc, 0, v101, vcc
	global_store_dwordx4 v[78:79], v[106:109], off offset:1024
	v_lshlrev_b32_e32 v78, 16, v68
	v_and_b32_e32 v79, 0xffff0000, v68
	v_pk_fma_f32 v[32:33], v[44:45], v[78:79], v[32:33]
	v_lshlrev_b32_e32 v44, 16, v48
	v_pk_add_f32 v[32:33], v[52:53], v[32:33]
	v_pk_mul_f32 v[52:53], v[56:57], v[104:105]
	v_mul_f32_e32 v36, 0xbfb8aa3b, v32
	v_mul_f32_e32 v37, 0xbfb8aa3b, v33
	v_exp_f32_e32 v36, v36
	v_exp_f32_e32 v37, v37
	v_and_b32_e32 v45, 0xffff0000, v48
	v_pk_fma_f32 v[40:41], v[40:41], v[114:115], v[52:53]
	v_add_f32_e32 v36, 1.0, v36
	v_add_f32_e32 v37, 1.0, v37
	v_rcp_f32_e32 v36, v36
	v_rcp_f32_e32 v37, v37
	v_pk_fma_f32 v[40:41], v[60:61], v[44:45], v[40:41]
	v_pk_mul_f32 v[32:33], v[32:33], v[36:37]
	v_lshlrev_b32_e32 v36, 16, v69
	v_and_b32_e32 v37, 0xffff0000, v69
	v_pk_fma_f32 v[34:35], v[46:47], v[36:37], v[34:35]
	v_pk_add_f32 v[40:41], v[64:65], v[40:41]
	v_pk_add_f32 v[34:35], v[54:55], v[34:35]
	v_pk_mul_f32 v[32:33], v[32:33], v[40:41]
	v_mul_f32_e32 v36, 0xbfb8aa3b, v34
	v_mul_f32_e32 v37, 0xbfb8aa3b, v35
	v_exp_f32_e32 v36, v36
	v_exp_f32_e32 v37, v37
	v_pk_mul_f32 v[40:41], v[58:59], v[102:103]
	v_add_f32_e32 v36, 1.0, v36
	v_add_f32_e32 v37, 1.0, v37
	v_rcp_f32_e32 v36, v36
	v_rcp_f32_e32 v37, v37
	v_pk_fma_f32 v[40:41], v[42:43], v[94:95], v[40:41]
	v_pk_mul_f32 v[34:35], v[34:35], v[36:37]
	v_lshlrev_b32_e32 v36, 16, v70
	v_and_b32_e32 v37, 0xffff0000, v70
	v_pk_fma_f32 v[0:1], v[12:13], v[36:37], v[0:1]
	v_lshlrev_b32_e32 v12, 16, v50
	v_pk_add_f32 v[0:1], v[16:17], v[0:1]
	v_pk_mul_f32 v[16:17], v[20:21], v[98:99]
	v_mul_f32_e32 v4, 0xbfb8aa3b, v0
	v_mul_f32_e32 v5, 0xbfb8aa3b, v1
	v_exp_f32_e32 v4, v4
	v_exp_f32_e32 v5, v5
	v_and_b32_e32 v13, 0xffff0000, v50
	v_pk_fma_f32 v[8:9], v[8:9], v[92:93], v[16:17]
	v_add_f32_e32 v4, 1.0, v4
	v_add_f32_e32 v5, 1.0, v5
	v_rcp_f32_e32 v4, v4
	v_rcp_f32_e32 v5, v5
	v_pk_fma_f32 v[8:9], v[24:25], v[12:13], v[8:9]
	v_pk_fma_f32 v[38:39], v[62:63], v[38:39], v[40:41]
	v_pk_add_f32 v[8:9], v[28:29], v[8:9]
	v_pk_mul_f32 v[0:1], v[0:1], v[4:5]
	v_pk_add_f32 v[38:39], v[66:67], v[38:39]
	v_pk_mul_f32 v[4:5], v[0:1], v[8:9]
	v_lshlrev_b32_e32 v0, 16, v71
	v_and_b32_e32 v1, 0xffff0000, v71
	v_pk_fma_f32 v[0:1], v[14:15], v[0:1], v[2:3]
	v_pk_mul_f32 v[8:9], v[22:23], v[74:75]
	v_pk_add_f32 v[0:1], v[18:19], v[0:1]
	v_pk_fma_f32 v[8:9], v[10:11], v[82:83], v[8:9]
	v_mul_f32_e32 v2, 0xbfb8aa3b, v0
	v_mul_f32_e32 v3, 0xbfb8aa3b, v1
	v_exp_f32_e32 v2, v2
	v_exp_f32_e32 v3, v3
	v_pk_fma_f32 v[6:7], v[26:27], v[6:7], v[8:9]
	v_pk_mul_f32 v[34:35], v[34:35], v[38:39]
	v_add_f32_e32 v2, 1.0, v2
	v_add_f32_e32 v3, 1.0, v3
	v_rcp_f32_e32 v2, v2
	v_rcp_f32_e32 v3, v3
	v_pk_add_f32 v[6:7], v[30:31], v[6:7]
	v_pk_mul_f32 v[0:1], v[0:1], v[2:3]
	v_cvt_pk_bf16_f32 v2, v4, v5
	v_add_co_u32_e32 v4, vcc, 0x14000, v100
	v_pk_mul_f32 v[6:7], v[0:1], v[6:7]
	s_nop 0
	v_addc_co_u32_e32 v5, vcc, 0, v101, vcc
	v_cmp_le_u32_e32 vcc, v215, v118
	s_nop 1
	v_cndmask_b32_e64 v216, 0, 1, vcc
	v_cmp_gt_u32_e32 vcc, 0x60000, v118
	s_nop 1
	v_cndmask_b32_e64 v217, 0, 1, vcc
	v_and_b32_e32 v216, v216, v217
	v_cmp_ne_u32_e32 vcc, 0, v216
	s_nop 1
	v_cndmask_b32_e32 v118, v118, v214, vcc
	v_cmp_lt_u64_e32 vcc, s[0:1], v[118:119]
	v_cvt_pk_bf16_f32 v0, v32, v33
	v_cvt_pk_bf16_f32 v1, v34, v35
	v_cvt_pk_bf16_f32 v3, v6, v7
	s_or_b64 s[16:17], vcc, s[16:17]
	global_store_dwordx4 v[4:5], v[0:3], off offset:2560
	s_andn2_b64 exec, exec, s[16:17]
	s_cbranch_execz .LBB0_306
